# permlane32_swap max-exchange in all 7 attention tile loops (MLA site also drops its 7-instruction lane-address recompute)
# speedup vs baseline: 1.0013x; 1.0013x over previous
; DI float fexp2(float x) { return __builtin_amdgcn_exp2f(x); }
; DI float max3f(float a, float b, float c) { float r; asm("v_max3_f32 %0, %1, %2, %3" : "=v"(r) : "v"(a), "v"(b), "v"(c)); return r; }
; DI float max2f(float a, float b) { float r; asm("v_max_f32_e32 %0, %1, %2" : "=v"(r) : "v"(a), "v"(b)); return r; }
;     ...
;             float mxa = max3f(s0[0], s1[0], s0[1]), mxb = max3f(s1[1], s0[2], s1[2]);
; #pragma unroll
;             for (int i = 3; i < 15; i += 2) { mxa = max3f(mxa, s0[i], s1[i]); mxb = max3f(mxb, s0[i + 1], s1[i + 1]); }
;             float mx = max3f(mxa, mxb, max2f(s0[15], s1[15]));
;             mx = max2f(mx, __shfl_xor(mx, 32));
;             if (__builtin_amdgcn_ballot_w64(mx - m > 8.0f) != 0ull) {
;                 const float mn = fmaxf(m, mx), mu_ = (mn == -INFINITY) ? 0.f : mn;
;                 const float alpha = fexp2(m - mu_); m = mn; l *= alpha;
; #pragma unroll
;                 for (int i = 0; i < 16; ++i) { o0[i] *= alpha; o1[i] *= alpha; }
;             }
.LBB0_153:
	v_max3_f32 v202, v98, v114, v99
	v_max3_f32 v203, v115, v100, v116
	v_max_f32_e32 v204, v113, v129
	s_mov_b32 s0, 0x41000000
	v_max3_f32 v202, v202, v101, v117
	v_max3_f32 v203, v203, v102, v118
	s_nop 0
	v_max3_f32 v202, v202, v103, v119
	v_max3_f32 v203, v203, v104, v120
	s_nop 0
	v_max3_f32 v202, v202, v105, v121
	v_max3_f32 v203, v203, v106, v122
	s_nop 0
	v_max3_f32 v202, v202, v107, v123
	v_max3_f32 v203, v203, v108, v124
	s_nop 0
	v_max3_f32 v202, v202, v109, v125
	v_max3_f32 v203, v203, v110, v126
	s_nop 0
	v_max3_f32 v202, v202, v111, v127
	v_max3_f32 v203, v203, v112, v128
	s_nop 0
	v_max3_f32 v202, v202, v203, v204
	v_mov_b32_e32 v203, v202
	s_nop 1
	v_permlane32_swap_b32_e32 v203, v202
	v_max_f32_e32 v214, v202, v203
	s_nop 0
	v_sub_f32_e32 v202, v214, v213
	v_cmp_lt_f32_e32 vcc, s0, v202
	s_cbranch_vccz .LBB0_155
	v_max_f32_e32 v202, v214, v214
	v_max_f32_e32 v203, v213, v213
	v_max_f32_e32 v203, v203, v202
	v_cmp_neq_f32_e32 vcc, s79, v203
	s_nop 1
	v_cndmask_b32_e32 v202, 0, v203, vcc
	v_sub_f32_e32 v202, v213, v202
	v_exp_f32_e32 v202, v202
	v_mov_b32_e32 v213, v203
	v_mul_f32_e32 v211, v211, v202
	v_pk_mul_f32 v[80:81], v[80:81], v[202:203] op_sel_hi:[1,0]
	v_pk_mul_f32 v[78:79], v[78:79], v[202:203] op_sel_hi:[1,0]
	v_pk_mul_f32 v[76:77], v[76:77], v[202:203] op_sel_hi:[1,0]
	v_pk_mul_f32 v[74:75], v[74:75], v[202:203] op_sel_hi:[1,0]
	v_pk_mul_f32 v[72:73], v[72:73], v[202:203] op_sel_hi:[1,0]
	v_pk_mul_f32 v[70:71], v[70:71], v[202:203] op_sel_hi:[1,0]
	v_pk_mul_f32 v[68:69], v[68:69], v[202:203] op_sel_hi:[1,0]
	v_pk_mul_f32 v[66:67], v[66:67], v[202:203] op_sel_hi:[1,0]
	v_pk_mul_f32 v[96:97], v[96:97], v[202:203] op_sel_hi:[1,0]
	v_pk_mul_f32 v[94:95], v[94:95], v[202:203] op_sel_hi:[1,0]
	v_pk_mul_f32 v[92:93], v[92:93], v[202:203] op_sel_hi:[1,0]
	v_pk_mul_f32 v[90:91], v[90:91], v[202:203] op_sel_hi:[1,0]
	v_pk_mul_f32 v[88:89], v[88:89], v[202:203] op_sel_hi:[1,0]
	v_pk_mul_f32 v[86:87], v[86:87], v[202:203] op_sel_hi:[1,0]
	v_pk_mul_f32 v[84:85], v[84:85], v[202:203] op_sel_hi:[1,0]
	v_pk_mul_f32 v[82:83], v[82:83], v[202:203] op_sel_hi:[1,0]

; DI float fexp2(float x) { return __builtin_amdgcn_exp2f(x); }
; DI float max3f(float a, float b, float c) { float r; asm("v_max3_f32 %0, %1, %2, %3" : "=v"(r) : "v"(a), "v"(b), "v"(c)); return r; }
; DI float max2f(float a, float b) { float r; asm("v_max_f32_e32 %0, %1, %2" : "=v"(r) : "v"(a), "v"(b)); return r; }
;     ...
;             float mxa = max3f(s0[0], s1[0], s0[1]), mxb = max3f(s1[1], s0[2], s1[2]);
; #pragma unroll
;             for (int i = 3; i < 15; i += 2) { mxa = max3f(mxa, s0[i], s1[i]); mxb = max3f(mxb, s0[i + 1], s1[i + 1]); }
;             float mx = max3f(mxa, mxb, max2f(s0[15], s1[15]));
;             mx = max2f(mx, __shfl_xor(mx, 32));
;             if (__builtin_amdgcn_ballot_w64(mx - m > 8.0f) != 0ull) {
;                 const float mn = fmaxf(m, mx), mu_ = (mn == -INFINITY) ? 0.f : mn;
;                 const float alpha = fexp2(m - mu_); m = mn; l *= alpha;
; #pragma unroll
;                 for (int i = 0; i < 16; ++i) { o0[i] *= alpha; o1[i] *= alpha; }
;             }
.LBB0_251:
	v_max3_f32 v146, v50, v34, v51
	v_max3_f32 v147, v35, v52, v36
	v_max_f32_e32 v148, v65, v49
	s_mov_b32 s1, 0x41000000
	v_max3_f32 v146, v146, v53, v37
	v_max3_f32 v147, v147, v54, v38
	s_nop 0
	v_max3_f32 v146, v146, v55, v39
	v_max3_f32 v147, v147, v56, v40
	s_nop 0
	v_max3_f32 v146, v146, v57, v41
	v_max3_f32 v147, v147, v58, v42
	s_nop 0
	v_max3_f32 v146, v146, v59, v43
	v_max3_f32 v147, v147, v60, v44
	s_nop 0
	v_max3_f32 v146, v146, v61, v45
	v_max3_f32 v147, v147, v62, v46
	s_nop 0
	v_max3_f32 v146, v146, v63, v47
	v_max3_f32 v147, v147, v64, v48
	s_nop 0
	v_max3_f32 v146, v146, v147, v148
	v_mov_b32_e32 v147, v146
	s_nop 1
	v_permlane32_swap_b32_e32 v147, v146
	v_max_f32_e32 v146, v146, v147
	s_nop 0
	v_sub_f32_e32 v147, v146, v145
	v_cmp_lt_f32_e32 vcc, s1, v147
	s_cbranch_vccz .LBB0_253
	v_max_f32_e32 v146, v146, v146
	v_max_f32_e32 v147, v145, v145
	v_max_f32_e32 v147, v147, v146
	v_cmp_neq_f32_e32 vcc, s79, v147
	s_nop 1
	v_cndmask_b32_e32 v146, 0, v147, vcc
	v_sub_f32_e32 v145, v145, v146
	v_exp_f32_e32 v146, v145
	v_mov_b32_e32 v145, v147
	v_mul_f32_e32 v144, v144, v146
	v_pk_mul_f32 v[32:33], v[32:33], v[146:147] op_sel_hi:[1,0]
	v_pk_mul_f32 v[30:31], v[30:31], v[146:147] op_sel_hi:[1,0]
	v_pk_mul_f32 v[28:29], v[28:29], v[146:147] op_sel_hi:[1,0]
	v_pk_mul_f32 v[26:27], v[26:27], v[146:147] op_sel_hi:[1,0]
	v_pk_mul_f32 v[24:25], v[24:25], v[146:147] op_sel_hi:[1,0]
	v_pk_mul_f32 v[22:23], v[22:23], v[146:147] op_sel_hi:[1,0]
	v_pk_mul_f32 v[20:21], v[20:21], v[146:147] op_sel_hi:[1,0]
	v_pk_mul_f32 v[18:19], v[18:19], v[146:147] op_sel_hi:[1,0]
	v_pk_mul_f32 v[16:17], v[16:17], v[146:147] op_sel_hi:[1,0]
	v_pk_mul_f32 v[14:15], v[14:15], v[146:147] op_sel_hi:[1,0]
	v_pk_mul_f32 v[12:13], v[12:13], v[146:147] op_sel_hi:[1,0]
	v_pk_mul_f32 v[10:11], v[10:11], v[146:147] op_sel_hi:[1,0]
	v_pk_mul_f32 v[8:9], v[8:9], v[146:147] op_sel_hi:[1,0]
	v_pk_mul_f32 v[6:7], v[6:7], v[146:147] op_sel_hi:[1,0]
	v_pk_mul_f32 v[4:5], v[4:5], v[146:147] op_sel_hi:[1,0]
	v_pk_mul_f32 v[2:3], v[2:3], v[146:147] op_sel_hi:[1,0]
